# GEMM3 phase start staggered: WGs with bx&4 sleep ~12us after seam 5 so the two halves' epilogue/final-pass memory bursts overlap the other half's MFMA; on top of v065
# baseline (speedup 1.0000x reference)
; #define fresh_tid() ((wave0 << 6) | lane_id_fresh())
; template <int COOP>
; __global__ void __launch_bounds__(512, 2) mega(Args a) {
;     ...
;     if (IN(6)) { const Ptrs P = mkptrs(ptab);
;         pg8::Gemm g{P.MG, P.WOT, T, D, D, D}; pg8::StaticOrder S; S.init(T, D, G, bx, 1, 4);
;         pg8::EpiG3 E{P.x, P.U, P.ssq, P.cnt};
;         pg8::gemm_phase(lds, g, S, E, fresh_tid());
.LBB0_541:
	s_or_b64 exec, exec, s[0:1]
	s_add_i32 s0, 0, 0x24000
	s_waitcnt lgkmcnt(0)
	v_mov_b32_e32 v0, s0
	s_barrier
	s_bitcmp1_b32 s2, 2
	s_cbranch_scc0 .Lstg6_skip
	s_sleep 127
	s_sleep 127
	s_sleep 127
.Lstg6_skip:
	ds_read_b64 v[4:5], v0
	s_add_i32 s0, 0, 0x24050
	v_mov_b32_e32 v0, s0
	s_add_i32 s0, 0, 0x24060
	ds_read_b128 v[0:3], v0
	s_waitcnt lgkmcnt(1)
	v_readfirstlane_b32 s12, v4
	v_mov_b32_e32 v4, s0
	v_readfirstlane_b32 s13, v5
	ds_read_b64 v[4:5], v4
	s_waitcnt lgkmcnt(1)
	v_readfirstlane_b32 s21, v1
	v_readfirstlane_b32 s20, v0
	v_mbcnt_lo_u32_b32 v8, -1, 0
	v_mbcnt_hi_u32_b32 v8, -1, v8
	v_cndmask_b32_e64 v1, 0, 1, s[6:7]
	v_or_b32_e32 v0, s33, v8
	v_readfirstlane_b32 s9, v3
	v_readfirstlane_b32 s8, v2
	s_waitcnt lgkmcnt(0)
	v_readfirstlane_b32 s11, v5
	v_readfirstlane_b32 s10, v4
	v_cmp_ne_u32_e64 s[0:1], 1, v1
	s_andn2_b64 vcc, exec, s[6:7]
	v_readfirstlane_b32 s6, v0
	s_cbranch_vccnz .LBB0_547
	s_and_b64 vcc, exec, s[38:39]
	s_cbranch_vccz .LBB0_544
	s_lshl_b32 s7, s65, 6
	s_cbranch_execz .LBB0_545
	s_branch .LBB0_546
